# grid barriers: the globally last XCD leader bumps all per-XCC generation words itself (one polling hop less for 7/8 of the workgroups); XCD leaders no longer add to their own
# speedup vs baseline: 1.0102x; 1.0033x over previous
.LBB0_141:
	s_or_b64 exec, exec, s[18:19]
	v_cvt_f32_u32_e32 v3, v0
	s_waitcnt vmcnt(0)
	v_readfirstlane_b32 s3, v2
	s_add_u32 s18, s50, 0x83500
	s_addc_u32 s19, s51, 0
	v_rcp_iflag_f32_e32 v3, v3
	v_add_u32_e32 v1, s3, v1
	v_add_u32_e32 v4, 1, v1
	s_mov_b64 s[20:21], -1
	v_mul_f32_e32 v2, 0x4f7ffffe, v3
	v_cvt_u32_f32_e32 v2, v2
	v_sub_u32_e32 v3, 0, v0
	v_mul_lo_u32 v3, v3, v2
	v_mul_hi_u32 v3, v2, v3
	v_add_u32_e32 v2, v2, v3
	v_mul_hi_u32 v2, v1, v2
	v_mul_lo_u32 v3, v2, v0
	v_sub_u32_e32 v1, v1, v3
	v_add_u32_e32 v5, 1, v2
	v_cmp_ge_u32_e32 vcc, v1, v0
	v_sub_u32_e32 v3, v1, v0
	s_nop 0
	v_cndmask_b32_e32 v2, v2, v5, vcc
	v_cndmask_b32_e32 v1, v1, v3, vcc
	v_add_u32_e32 v3, 1, v2
	v_cmp_ge_u32_e32 vcc, v1, v0
	s_nop 1
	v_cndmask_b32_e32 v2, v2, v3, vcc
	v_mul_lo_u32 v1, v0, v2
	v_add_u32_e32 v0, v1, v0
	v_cmp_ne_u32_e32 vcc, v4, v0
	v_mov_b64_e32 v[0:1], s[18:19]
	s_cbranch_vccnz .Lxg_skip_0
	v_mov_b32_e32 v20, 0x2400
	v_mov_b32_e32 v21, 1
	global_atomic_add v20, v21, s[54:55]
	global_atomic_add v20, v21, s[54:55] offset:256
	global_atomic_add v20, v21, s[54:55] offset:512
	global_atomic_add v20, v21, s[54:55] offset:768
	global_atomic_add v20, v21, s[54:55] offset:1024
	global_atomic_add v20, v21, s[54:55] offset:1280
	global_atomic_add v20, v21, s[54:55] offset:1536
	global_atomic_add v20, v21, s[54:55] offset:1792
	global_atomic_add v20, v21, s[54:55] offset:2048
	global_atomic_add v20, v21, s[54:55] offset:2304
	global_atomic_add v20, v21, s[54:55] offset:2560
	global_atomic_add v20, v21, s[54:55] offset:2816
	global_atomic_add v20, v21, s[54:55] offset:3072
	global_atomic_add v20, v21, s[54:55] offset:3328
	global_atomic_add v20, v21, s[54:55] offset:3584
	global_atomic_add v20, v21, s[54:55] offset:3840
.Lxg_skip_0:
	s_and_saveexec_b64 s[16:17], vcc
	s_cbranch_execz .LBB0_153
	v_mov_b32_e32 v0, 0
	global_load_dword v1, v0, s[18:19] sc1
	s_mov_b64 s[24:25], 0
	s_waitcnt vmcnt(0)
	v_cmp_eq_u32_e32 vcc, v1, v2
	s_and_saveexec_b64 s[22:23], vcc
	s_cbranch_execz .LBB0_152
	s_add_u32 s20, s50, 0x80200
	s_addc_u32 s21, s51, 0
	s_mov_b32 s3, 1
	s_branch .LBB0_145

.LBB0_155:
	s_or_b64 exec, exec, s[16:17]
	s_mov_b64 s[16:17], exec
	v_mbcnt_lo_u32_b32 v0, s16, 0
	v_mbcnt_hi_u32_b32 v0, s17, v0
	v_cmp_eq_u32_e32 vcc, 0, v0
	s_waitcnt vmcnt(0)
	s_and_saveexec_b64 s[18:19], vcc
	s_cbranch_execz .LBB0_157
	s_bcnt1_i32_b64 s3, s[16:17]
	v_mov_b32_e32 v0, 0x2000
	v_mov_b32_e32 v1, s3
	s_nop 0

.LBB0_322:
	s_or_b64 exec, exec, s[16:17]
	v_cvt_f32_u32_e32 v3, v0
	s_waitcnt vmcnt(0)
	v_readfirstlane_b32 s10, v2
	s_add_u32 s16, s50, 0x83500
	s_addc_u32 s17, s51, 0
	v_rcp_iflag_f32_e32 v3, v3
	v_add_u32_e32 v1, s10, v1
	v_add_u32_e32 v4, 1, v1
	s_mov_b64 s[18:19], -1
	v_mul_f32_e32 v2, 0x4f7ffffe, v3
	v_cvt_u32_f32_e32 v2, v2
	v_sub_u32_e32 v3, 0, v0
	v_mul_lo_u32 v3, v3, v2
	v_mul_hi_u32 v3, v2, v3
	v_add_u32_e32 v2, v2, v3
	v_mul_hi_u32 v2, v1, v2
	v_mul_lo_u32 v3, v2, v0
	v_sub_u32_e32 v1, v1, v3
	v_add_u32_e32 v5, 1, v2
	v_cmp_ge_u32_e32 vcc, v1, v0
	v_sub_u32_e32 v3, v1, v0
	s_nop 0
	v_cndmask_b32_e32 v2, v2, v5, vcc
	v_cndmask_b32_e32 v1, v1, v3, vcc
	v_add_u32_e32 v3, 1, v2
	v_cmp_ge_u32_e32 vcc, v1, v0
	s_nop 1
	v_cndmask_b32_e32 v2, v2, v3, vcc
	v_mul_lo_u32 v1, v0, v2
	v_add_u32_e32 v0, v1, v0
	v_cmp_ne_u32_e32 vcc, v4, v0
	v_mov_b64_e32 v[0:1], s[16:17]
	s_cbranch_vccnz .Lxg_skip_1
	v_mov_b32_e32 v20, 0x2400
	v_mov_b32_e32 v21, 1
	global_atomic_add v20, v21, s[54:55]
	global_atomic_add v20, v21, s[54:55] offset:256
	global_atomic_add v20, v21, s[54:55] offset:512
	global_atomic_add v20, v21, s[54:55] offset:768
	global_atomic_add v20, v21, s[54:55] offset:1024
	global_atomic_add v20, v21, s[54:55] offset:1280
	global_atomic_add v20, v21, s[54:55] offset:1536
	global_atomic_add v20, v21, s[54:55] offset:1792
	global_atomic_add v20, v21, s[54:55] offset:2048
	global_atomic_add v20, v21, s[54:55] offset:2304
	global_atomic_add v20, v21, s[54:55] offset:2560
	global_atomic_add v20, v21, s[54:55] offset:2816
	global_atomic_add v20, v21, s[54:55] offset:3072
	global_atomic_add v20, v21, s[54:55] offset:3328
	global_atomic_add v20, v21, s[54:55] offset:3584
	global_atomic_add v20, v21, s[54:55] offset:3840
.Lxg_skip_1:
	s_and_saveexec_b64 s[10:11], vcc
	s_cbranch_execz .LBB0_334
	v_mov_b32_e32 v0, 0
	global_load_dword v1, v0, s[16:17] sc1
	s_mov_b64 s[22:23], 0
	s_waitcnt vmcnt(0)
	v_cmp_eq_u32_e32 vcc, v1, v2
	s_and_saveexec_b64 s[20:21], vcc
	s_cbranch_execz .LBB0_333
	s_add_u32 s18, s50, 0x80200
	s_addc_u32 s19, s51, 0
	s_mov_b32 s34, 1
	s_branch .LBB0_326

.LBB0_336:
	s_or_b64 exec, exec, s[10:11]
	s_mov_b64 s[10:11], exec
	v_mbcnt_lo_u32_b32 v0, s10, 0
	v_mbcnt_hi_u32_b32 v0, s11, v0
	v_cmp_eq_u32_e32 vcc, 0, v0
	s_waitcnt vmcnt(0)
	s_and_saveexec_b64 s[16:17], vcc
	s_cbranch_execz .LBB0_338
	s_bcnt1_i32_b64 s10, s[10:11]
	v_mov_b32_e32 v0, 0x2000
	v_mov_b32_e32 v1, s10
	s_nop 0

.LBB0_586:
	s_or_b64 exec, exec, s[14:15]
	v_cvt_f32_u32_e32 v3, v0
	s_waitcnt vmcnt(0)
	v_readfirstlane_b32 s10, v2
	s_add_u32 s14, s50, 0x83500
	s_addc_u32 s15, s51, 0
	v_rcp_iflag_f32_e32 v3, v3
	v_add_u32_e32 v1, s10, v1
	v_add_u32_e32 v4, 1, v1
	s_mov_b64 s[16:17], -1
	v_mul_f32_e32 v2, 0x4f7ffffe, v3
	v_cvt_u32_f32_e32 v2, v2
	v_sub_u32_e32 v3, 0, v0
	v_mul_lo_u32 v3, v3, v2
	v_mul_hi_u32 v3, v2, v3
	v_add_u32_e32 v2, v2, v3
	v_mul_hi_u32 v2, v1, v2
	v_mul_lo_u32 v3, v2, v0
	v_sub_u32_e32 v1, v1, v3
	v_add_u32_e32 v5, 1, v2
	v_cmp_ge_u32_e32 vcc, v1, v0
	v_sub_u32_e32 v3, v1, v0
	s_nop 0
	v_cndmask_b32_e32 v2, v2, v5, vcc
	v_cndmask_b32_e32 v1, v1, v3, vcc
	v_add_u32_e32 v3, 1, v2
	v_cmp_ge_u32_e32 vcc, v1, v0
	s_nop 1
	v_cndmask_b32_e32 v2, v2, v3, vcc
	v_mul_lo_u32 v1, v0, v2
	v_add_u32_e32 v0, v1, v0
	v_cmp_ne_u32_e32 vcc, v4, v0
	v_mov_b64_e32 v[0:1], s[14:15]
	s_cbranch_vccnz .Lxg_skip_3
	v_mov_b32_e32 v20, 0x2400
	v_mov_b32_e32 v21, 1
	global_atomic_add v20, v21, s[54:55]
	global_atomic_add v20, v21, s[54:55] offset:256
	global_atomic_add v20, v21, s[54:55] offset:512
	global_atomic_add v20, v21, s[54:55] offset:768
	global_atomic_add v20, v21, s[54:55] offset:1024
	global_atomic_add v20, v21, s[54:55] offset:1280
	global_atomic_add v20, v21, s[54:55] offset:1536
	global_atomic_add v20, v21, s[54:55] offset:1792
	global_atomic_add v20, v21, s[54:55] offset:2048
	global_atomic_add v20, v21, s[54:55] offset:2304
	global_atomic_add v20, v21, s[54:55] offset:2560
	global_atomic_add v20, v21, s[54:55] offset:2816
	global_atomic_add v20, v21, s[54:55] offset:3072
	global_atomic_add v20, v21, s[54:55] offset:3328
	global_atomic_add v20, v21, s[54:55] offset:3584
	global_atomic_add v20, v21, s[54:55] offset:3840
.Lxg_skip_3:
	s_and_saveexec_b64 s[10:11], vcc
	s_cbranch_execz .LBB0_598
	v_mov_b32_e32 v0, 0
	global_load_dword v1, v0, s[14:15] sc1
	s_mov_b64 s[20:21], 0
	s_waitcnt vmcnt(0)
	v_cmp_eq_u32_e32 vcc, v1, v2
	s_and_saveexec_b64 s[18:19], vcc
	s_cbranch_execz .LBB0_597
	s_add_u32 s16, s50, 0x80200
	s_addc_u32 s17, s51, 0
	s_mov_b32 s13, 1
	s_branch .LBB0_590

.LBB0_600:
	s_or_b64 exec, exec, s[10:11]
	s_mov_b64 s[10:11], exec
	v_mbcnt_lo_u32_b32 v0, s10, 0
	v_mbcnt_hi_u32_b32 v0, s11, v0
	v_cmp_eq_u32_e32 vcc, 0, v0
	s_waitcnt vmcnt(0)
	s_and_saveexec_b64 s[14:15], vcc
	s_cbranch_execz .LBB0_602
	s_bcnt1_i32_b64 s10, s[10:11]
	v_mov_b32_e32 v0, 0x2000
	v_mov_b32_e32 v1, s10
	s_nop 0

.LBB0_914:
	s_or_b64 exec, exec, s[10:11]
	v_cvt_f32_u32_e32 v3, v0
	s_waitcnt vmcnt(0)
	v_readfirstlane_b32 s8, v2
	s_add_u32 s10, s50, 0x83500
	s_addc_u32 s11, s51, 0
	v_rcp_iflag_f32_e32 v3, v3
	v_add_u32_e32 v1, s8, v1
	v_add_u32_e32 v4, 1, v1
	s_mov_b64 s[12:13], -1
	v_mul_f32_e32 v2, 0x4f7ffffe, v3
	v_cvt_u32_f32_e32 v2, v2
	v_sub_u32_e32 v3, 0, v0
	v_mul_lo_u32 v3, v3, v2
	v_mul_hi_u32 v3, v2, v3
	v_add_u32_e32 v2, v2, v3
	v_mul_hi_u32 v2, v1, v2
	v_mul_lo_u32 v3, v2, v0
	v_sub_u32_e32 v1, v1, v3
	v_add_u32_e32 v5, 1, v2
	v_cmp_ge_u32_e32 vcc, v1, v0
	v_sub_u32_e32 v3, v1, v0
	s_nop 0
	v_cndmask_b32_e32 v2, v2, v5, vcc
	v_cndmask_b32_e32 v1, v1, v3, vcc
	v_add_u32_e32 v3, 1, v2
	v_cmp_ge_u32_e32 vcc, v1, v0
	s_nop 1
	v_cndmask_b32_e32 v2, v2, v3, vcc
	v_mul_lo_u32 v1, v0, v2
	v_add_u32_e32 v0, v1, v0
	v_cmp_ne_u32_e32 vcc, v4, v0
	v_mov_b64_e32 v[0:1], s[10:11]
	s_cbranch_vccnz .Lxg_skip_4
	v_mov_b32_e32 v20, 0x2400
	v_mov_b32_e32 v21, 1
	global_atomic_add v20, v21, s[54:55]
	global_atomic_add v20, v21, s[54:55] offset:256
	global_atomic_add v20, v21, s[54:55] offset:512
	global_atomic_add v20, v21, s[54:55] offset:768
	global_atomic_add v20, v21, s[54:55] offset:1024
	global_atomic_add v20, v21, s[54:55] offset:1280
	global_atomic_add v20, v21, s[54:55] offset:1536
	global_atomic_add v20, v21, s[54:55] offset:1792
	global_atomic_add v20, v21, s[54:55] offset:2048
	global_atomic_add v20, v21, s[54:55] offset:2304
	global_atomic_add v20, v21, s[54:55] offset:2560
	global_atomic_add v20, v21, s[54:55] offset:2816
	global_atomic_add v20, v21, s[54:55] offset:3072
	global_atomic_add v20, v21, s[54:55] offset:3328
	global_atomic_add v20, v21, s[54:55] offset:3584
	global_atomic_add v20, v21, s[54:55] offset:3840
.Lxg_skip_4:
	s_and_saveexec_b64 s[8:9], vcc
	s_cbranch_execz .LBB0_926
	v_mov_b32_e32 v0, 0
	global_load_dword v1, v0, s[10:11] sc1
	s_mov_b64 s[16:17], 0
	s_waitcnt vmcnt(0)
	v_cmp_eq_u32_e32 vcc, v1, v2
	s_and_saveexec_b64 s[14:15], vcc
	s_cbranch_execz .LBB0_925
	s_add_u32 s12, s50, 0x80200
	s_addc_u32 s13, s51, 0
	s_mov_b32 s26, 1
	s_branch .LBB0_918

.LBB0_928:
	s_or_b64 exec, exec, s[8:9]
	s_mov_b64 s[8:9], exec
	v_mbcnt_lo_u32_b32 v0, s8, 0
	v_mbcnt_hi_u32_b32 v0, s9, v0
	v_cmp_eq_u32_e32 vcc, 0, v0
	s_waitcnt vmcnt(0)
	s_and_saveexec_b64 s[10:11], vcc
	s_cbranch_execz .LBB0_930
	s_bcnt1_i32_b64 s8, s[8:9]
	v_mov_b32_e32 v0, 0x2000
	v_mov_b32_e32 v1, s8
	s_nop 0

.LBB0_1041:
	s_or_b64 exec, exec, s[16:17]
	v_cvt_f32_u32_e32 v3, v0
	s_waitcnt vmcnt(0)
	v_readfirstlane_b32 s14, v2
	s_add_u32 s16, s50, 0x83500
	s_addc_u32 s17, s51, 0
	v_rcp_iflag_f32_e32 v3, v3
	v_add_u32_e32 v1, s14, v1
	v_add_u32_e32 v4, 1, v1
	s_mov_b64 s[18:19], -1
	v_mul_f32_e32 v2, 0x4f7ffffe, v3
	v_cvt_u32_f32_e32 v2, v2
	v_sub_u32_e32 v3, 0, v0
	v_mul_lo_u32 v3, v3, v2
	v_mul_hi_u32 v3, v2, v3
	v_add_u32_e32 v2, v2, v3
	v_mul_hi_u32 v2, v1, v2
	v_mul_lo_u32 v3, v2, v0
	v_sub_u32_e32 v1, v1, v3
	v_add_u32_e32 v5, 1, v2
	v_cmp_ge_u32_e32 vcc, v1, v0
	v_sub_u32_e32 v3, v1, v0
	s_nop 0
	v_cndmask_b32_e32 v2, v2, v5, vcc
	v_cndmask_b32_e32 v1, v1, v3, vcc
	v_add_u32_e32 v3, 1, v2
	v_cmp_ge_u32_e32 vcc, v1, v0
	s_nop 1
	v_cndmask_b32_e32 v2, v2, v3, vcc
	v_mul_lo_u32 v1, v0, v2
	v_add_u32_e32 v0, v1, v0
	v_cmp_ne_u32_e32 vcc, v4, v0
	v_mov_b64_e32 v[0:1], s[16:17]
	s_cbranch_vccnz .Lxg_skip_5
	v_mov_b32_e32 v20, 0x2400
	v_mov_b32_e32 v21, 1
	global_atomic_add v20, v21, s[54:55]
	global_atomic_add v20, v21, s[54:55] offset:256
	global_atomic_add v20, v21, s[54:55] offset:512
	global_atomic_add v20, v21, s[54:55] offset:768
	global_atomic_add v20, v21, s[54:55] offset:1024
	global_atomic_add v20, v21, s[54:55] offset:1280
	global_atomic_add v20, v21, s[54:55] offset:1536
	global_atomic_add v20, v21, s[54:55] offset:1792
	global_atomic_add v20, v21, s[54:55] offset:2048
	global_atomic_add v20, v21, s[54:55] offset:2304
	global_atomic_add v20, v21, s[54:55] offset:2560
	global_atomic_add v20, v21, s[54:55] offset:2816
	global_atomic_add v20, v21, s[54:55] offset:3072
	global_atomic_add v20, v21, s[54:55] offset:3328
	global_atomic_add v20, v21, s[54:55] offset:3584
	global_atomic_add v20, v21, s[54:55] offset:3840
.Lxg_skip_5:
	s_and_saveexec_b64 s[14:15], vcc
	s_cbranch_execz .LBB0_1053
	v_mov_b32_e32 v0, 0
	global_load_dword v1, v0, s[16:17] sc1
	s_mov_b64 s[22:23], 0
	s_waitcnt vmcnt(0)
	v_cmp_eq_u32_e32 vcc, v1, v2
	s_and_saveexec_b64 s[20:21], vcc
	s_cbranch_execz .LBB0_1052
	s_add_u32 s18, s50, 0x80200
	s_addc_u32 s19, s51, 0
	s_mov_b32 s34, 1
	s_branch .LBB0_1045

.LBB0_1055:
	s_or_b64 exec, exec, s[14:15]
	s_mov_b64 s[14:15], exec
	v_mbcnt_lo_u32_b32 v0, s14, 0
	v_mbcnt_hi_u32_b32 v0, s15, v0
	v_cmp_eq_u32_e32 vcc, 0, v0
	s_waitcnt vmcnt(0)
	s_and_saveexec_b64 s[16:17], vcc
	s_cbranch_execz .LBB0_1057
	s_bcnt1_i32_b64 s14, s[14:15]
	v_mov_b32_e32 v0, 0x2000
	v_mov_b32_e32 v1, s14
	s_nop 0

.LBB0_1219:
	s_or_b64 exec, exec, s[12:13]
	v_cvt_f32_u32_e32 v3, v0
	s_waitcnt vmcnt(0)
	v_readfirstlane_b32 s10, v2
	s_add_u32 s12, s50, 0x83500
	s_addc_u32 s13, s51, 0
	v_rcp_iflag_f32_e32 v3, v3
	v_add_u32_e32 v1, s10, v1
	v_add_u32_e32 v4, 1, v1
	s_mov_b64 s[14:15], -1
	v_mul_f32_e32 v2, 0x4f7ffffe, v3
	v_cvt_u32_f32_e32 v2, v2
	v_sub_u32_e32 v3, 0, v0
	v_mul_lo_u32 v3, v3, v2
	v_mul_hi_u32 v3, v2, v3
	v_add_u32_e32 v2, v2, v3
	v_mul_hi_u32 v2, v1, v2
	v_mul_lo_u32 v3, v2, v0
	v_sub_u32_e32 v1, v1, v3
	v_add_u32_e32 v5, 1, v2
	v_cmp_ge_u32_e32 vcc, v1, v0
	v_sub_u32_e32 v3, v1, v0
	s_nop 0
	v_cndmask_b32_e32 v2, v2, v5, vcc
	v_cndmask_b32_e32 v1, v1, v3, vcc
	v_add_u32_e32 v3, 1, v2
	v_cmp_ge_u32_e32 vcc, v1, v0
	s_nop 1
	v_cndmask_b32_e32 v2, v2, v3, vcc
	v_mul_lo_u32 v1, v0, v2
	v_add_u32_e32 v0, v1, v0
	v_cmp_ne_u32_e32 vcc, v4, v0
	v_mov_b64_e32 v[0:1], s[12:13]
	s_cbranch_vccnz .Lxg_skip_6
	v_mov_b32_e32 v20, 0x2400
	v_mov_b32_e32 v21, 1
	global_atomic_add v20, v21, s[54:55]
	global_atomic_add v20, v21, s[54:55] offset:256
	global_atomic_add v20, v21, s[54:55] offset:512
	global_atomic_add v20, v21, s[54:55] offset:768
	global_atomic_add v20, v21, s[54:55] offset:1024
	global_atomic_add v20, v21, s[54:55] offset:1280
	global_atomic_add v20, v21, s[54:55] offset:1536
	global_atomic_add v20, v21, s[54:55] offset:1792
	global_atomic_add v20, v21, s[54:55] offset:2048
	global_atomic_add v20, v21, s[54:55] offset:2304
	global_atomic_add v20, v21, s[54:55] offset:2560
	global_atomic_add v20, v21, s[54:55] offset:2816
	global_atomic_add v20, v21, s[54:55] offset:3072
	global_atomic_add v20, v21, s[54:55] offset:3328
	global_atomic_add v20, v21, s[54:55] offset:3584
	global_atomic_add v20, v21, s[54:55] offset:3840
.Lxg_skip_6:
	s_and_saveexec_b64 s[10:11], vcc
	s_cbranch_execz .LBB0_1231
	v_mov_b32_e32 v0, 0
	global_load_dword v1, v0, s[12:13] sc1
	s_mov_b64 s[18:19], 0
	s_waitcnt vmcnt(0)
	v_cmp_eq_u32_e32 vcc, v1, v2
	s_and_saveexec_b64 s[16:17], vcc
	s_cbranch_execz .LBB0_1230
	s_add_u32 s14, s50, 0x80200
	s_addc_u32 s15, s51, 0
	s_mov_b32 s28, 1
	s_branch .LBB0_1223

.LBB0_1233:
	s_or_b64 exec, exec, s[10:11]
	s_mov_b64 s[10:11], exec
	v_mbcnt_lo_u32_b32 v0, s10, 0
	v_mbcnt_hi_u32_b32 v0, s11, v0
	v_cmp_eq_u32_e32 vcc, 0, v0
	s_waitcnt vmcnt(0)
	s_and_saveexec_b64 s[12:13], vcc
	s_cbranch_execz .LBB0_1235
	s_bcnt1_i32_b64 s10, s[10:11]
	v_mov_b32_e32 v0, 0x2000
	v_mov_b32_e32 v1, s10
	s_nop 0

.Lxg_skip_7:
	s_and_saveexec_b64 s[10:11], vcc
	s_cbranch_execz .LBB0_1335
	v_mov_b32_e32 v0, 0
	global_load_dword v1, v0, s[14:15] sc1
	s_mov_b64 s[20:21], 0
	s_waitcnt vmcnt(0)
	v_cmp_eq_u32_e32 vcc, v1, v2
	s_and_saveexec_b64 s[18:19], vcc
	s_cbranch_execz .LBB0_1334
	s_add_u32 s16, s50, 0x80200
	s_addc_u32 s17, s51, 0
	s_mov_b32 s30, 1
	s_branch .LBB0_1327
